# K-loop head aligned to 64 B
# baseline (speedup 1.0000x reference)
; template <class Epi, class Sched, bool ALIGN_EPI = false, bool SP2 = false>
; __device__ __forceinline__ void gemm_phase(PG8_LAS unsigned char* lds, const Gemm g, const Sched& S, const Epi& E) {
;     ...
; #pragma unroll
;     for (int a = 0; a < 2; ++a)
; #pragma unroll
;         for (int b = 0; b < 2; ++b)
; #pragma unroll
;             for (int m = 0; m < 4; ++m)
; #pragma unroll
;                 for (int n = 0; n < 2; ++n) acc[a][b][m][n] = (f32x4){0.f, 0.f, 0.f, 0.f};
.LBB0_205:
	v_readlane_b32 s28, v255, 0
	v_readlane_b32 s29, v255, 1
	s_andn2_b64 vcc, exec, s[28:29]
	s_cbranch_vccnz .LBB0_208
	s_add_u32 s28, s6, 0x100
	s_addc_u32 s29, s7, 0
	s_add_u32 s6, s16, 0x80
	v_mov_b32_e32 v0, 0
	s_addc_u32 s7, s17, 0
	s_mov_b32 s16, 0
	v_mov_b32_e32 v1, v0
	v_mov_b32_e32 v2, v0
	v_mov_b32_e32 v3, v0
	v_mov_b32_e32 v4, v0
	v_mov_b32_e32 v5, v0
	v_mov_b32_e32 v6, v0
	v_mov_b32_e32 v7, v0
	v_mov_b32_e32 v16, v0
	v_mov_b32_e32 v17, v0
	v_mov_b32_e32 v18, v0
	v_mov_b32_e32 v19, v0
	v_mov_b32_e32 v20, v0
	v_mov_b32_e32 v21, v0
	v_mov_b32_e32 v22, v0
	v_mov_b32_e32 v23, v0
	v_mov_b32_e32 v32, v0
	v_mov_b32_e32 v33, v0
	v_mov_b32_e32 v34, v0
	v_mov_b32_e32 v35, v0
	v_mov_b32_e32 v36, v0
	v_mov_b32_e32 v37, v0
	v_mov_b32_e32 v38, v0
	v_mov_b32_e32 v39, v0
	v_mov_b32_e32 v48, v0
	v_mov_b32_e32 v49, v0
	v_mov_b32_e32 v50, v0
	v_mov_b32_e32 v51, v0
	v_mov_b32_e32 v52, v0
	v_mov_b32_e32 v53, v0
	v_mov_b32_e32 v54, v0
	v_mov_b32_e32 v55, v0
	v_mov_b32_e32 v8, v0
	v_mov_b32_e32 v9, v0
	v_mov_b32_e32 v10, v0
	v_mov_b32_e32 v11, v0
	v_mov_b32_e32 v12, v0
	v_mov_b32_e32 v13, v0
	v_mov_b32_e32 v14, v0
	v_mov_b32_e32 v15, v0
	v_mov_b32_e32 v24, v0
	v_mov_b32_e32 v25, v0
	v_mov_b32_e32 v26, v0
	v_mov_b32_e32 v27, v0
	v_mov_b32_e32 v28, v0
	v_mov_b32_e32 v29, v0
	v_mov_b32_e32 v30, v0
	v_mov_b32_e32 v31, v0
	v_mov_b32_e32 v40, v0
	v_mov_b32_e32 v41, v0
	v_mov_b32_e32 v42, v0
	v_mov_b32_e32 v43, v0
	v_mov_b32_e32 v44, v0
	v_mov_b32_e32 v45, v0
	v_mov_b32_e32 v46, v0
	v_mov_b32_e32 v47, v0
	v_mov_b32_e32 v56, v0
	v_mov_b32_e32 v57, v0
	v_mov_b32_e32 v58, v0
	v_mov_b32_e32 v59, v0
	v_mov_b32_e32 v60, v0
	v_mov_b32_e32 v61, v0
	v_mov_b32_e32 v62, v0
	v_mov_b32_e32 v63, v0
	v_mov_b32_e32 v68, v0
	v_mov_b32_e32 v69, v0
	v_mov_b32_e32 v70, v0
	v_mov_b32_e32 v71, v0
	v_mov_b32_e32 v72, v0
	v_mov_b32_e32 v73, v0
	v_mov_b32_e32 v74, v0
	v_mov_b32_e32 v75, v0
	v_mov_b32_e32 v84, v0
	v_mov_b32_e32 v85, v0
	v_mov_b32_e32 v86, v0
	v_mov_b32_e32 v87, v0
	v_mov_b32_e32 v88, v0
	v_mov_b32_e32 v89, v0
	s_waitcnt vmcnt(0)
	v_mov_b32_e32 v90, v0
	v_mov_b32_e32 v91, v0
	v_mov_b32_e32 v100, v0
	v_mov_b32_e32 v101, v0
	v_mov_b32_e32 v102, v0
	v_mov_b32_e32 v103, v0
	v_mov_b32_e32 v104, v0
	v_mov_b32_e32 v105, v0
	v_mov_b32_e32 v106, v0
	v_mov_b32_e32 v107, v0
	v_mov_b32_e32 v116, v0
	v_mov_b32_e32 v117, v0
	v_mov_b32_e32 v118, v0
	v_mov_b32_e32 v119, v0
	v_mov_b32_e32 v120, v0
	v_mov_b32_e32 v121, v0
	v_mov_b32_e32 v122, v0
	v_mov_b32_e32 v123, v0
	v_mov_b32_e32 v76, v0
	v_mov_b32_e32 v77, v0
	v_mov_b32_e32 v78, v0
	v_mov_b32_e32 v79, v0
	v_mov_b32_e32 v80, v0
	v_mov_b32_e32 v81, v0
	v_mov_b32_e32 v82, v0
	v_mov_b32_e32 v83, v0
	v_mov_b32_e32 v92, v0
	v_mov_b32_e32 v93, v0
	v_mov_b32_e32 v94, v0
	v_mov_b32_e32 v95, v0
	v_mov_b32_e32 v96, v0
	v_mov_b32_e32 v97, v0
	v_mov_b32_e32 v98, v0
	v_mov_b32_e32 v99, v0
	v_mov_b32_e32 v108, v0
	v_mov_b32_e32 v109, v0
	v_mov_b32_e32 v110, v0
	v_mov_b32_e32 v111, v0
	v_mov_b32_e32 v112, v0
	v_mov_b32_e32 v113, v0
	v_mov_b32_e32 v114, v0
	v_mov_b32_e32 v115, v0
	v_mov_b32_e32 v124, v0
	v_mov_b32_e32 v125, v0
	v_mov_b32_e32 v126, v0
	v_mov_b32_e32 v127, v0
	v_mov_b32_e32 v128, v0
	v_mov_b32_e32 v129, v0
	v_mov_b32_e32 v130, v0
	v_mov_b32_e32 v131, v0
	v_add_u32_e32 v236, 0x10000, v209
	v_add_u32_e32 v237, 0x14000, v209
	v_add_u32_e32 v238, 0x18000, v209
	v_add_u32_e32 v239, 0x1c000, v209
	.p2align 6
